# DSA indexer key cache stored in MFMA-fragment order per 32-key tile (coalesced 1 KiB fragment loads) + exact top-k bisection stops once exactly 256 keys are isolated
# speedup vs baseline: 1.0647x; 1.0502x over previous
;   __device__ __forceinline__ u16* P() const { return (u16*)(ws + O_P); }
;   __device__ __forceinline__ u16* KIDX() const { return (u16*)(ws + O_KIDX); }
;   __device__ __forceinline__ u16* CKV() const { return (u16*)(ws + O_CKV); }
;   __device__ __forceinline__ float* WIDX() const { return (float*)(ws + O_WIDX); }
; DI int ltid() { int t = threadIdx.x; asm volatile("" : "+v"(t)); return t; }
; DI float bf2f(u16 h) { return __uint_as_float(((u32)h) << 16); }
; DI float bflo(u32 v) { return __uint_as_float(v << 16); }
; DI float bfhi(u32 v) { return __uint_as_float(v & 0xffff0000u); }
; DI void dsa_kprep_item(const Params& p, int l, int it) {
;   const int ln = ltid() & 63, w = ltid() >> 6;
;   const float g0 = p.c_kv_norm_g[l * 128 + 2 * ln], g1 = p.c_kv_norm_g[l * 128 + 2 * ln + 1];
;   const float kg = p.c_kidx_g[l * 64 + ln], kb = p.c_kidx_b[l * 64 + ln];
;   for (int i = 0; i < 8; ++i) {
;     const size_t tok = (size_t)it * 64 + w * 8 + i;
;     const u16* pr = p.P() + tok * PC;
;     const u32 v = *(const u32*)(pr + CKVc + 2 * ln);
;     const float a = bflo(v), b = bfhi(v);
;     float ss = a * a + b * b;
; #pragma unroll
;     for (int o = 32; o; o >>= 1) ss += __shfl_xor(ss, o);
;     const float rs = rsqrtf(ss * (1.f / 128.f) + EPS);
;     *(u32*)(p.CKV() + tok * 128 + 2 * ln) = pack2(a * rs * g0, b * rs * g1);
;     const float k = bf2f(pr[CKI + ln]);
;     float s = k;
; #pragma unroll
;     for (int o = 32; o; o >>= 1) s += __shfl_xor(s, o);
;     const float mu = s * (1.f / 64.f);
;     float q = (k - mu) * (k - mu);
; #pragma unroll
;     for (int o = 32; o; o >>= 1) q += __shfl_xor(q, o);
;     p.KIDX()[tok * 64 + ln] = f2bf((k - mu) * rsqrtf(q * (1.f / 64.f) + EPS) * kg + kb);
;     if (ln < 8) p.WIDX()[tok * 8 + ln] = bf2f(pr[CWI + ln]) * 0.04419417382f;
;   }
.LBB0_241:
	s_cmpk_gt_i32 s18, 0x3ff
	s_mov_b64 s[0:1], -1
	s_cbranch_scc0 .LBB0_247
	v_mov_b32_e32 v0, v171
	v_readlane_b32 s36, v253, 16
	v_and_b32_e32 v8, 63, v0
	v_lshlrev_b32_e32 v23, 1, v8
	v_or_b32_e32 v0, s19, v23
	v_readlane_b32 s40, v253, 20
	v_readlane_b32 s41, v253, 21
	v_readlane_b32 s42, v253, 22
	v_readlane_b32 s43, v253, 23
	v_lshl_add_u64 v[2:3], v[0:1], 2, s[40:41]
	v_or_b32_e32 v0, s20, v8
	v_readlane_b32 s44, v253, 24
	v_readlane_b32 s45, v253, 25
	v_lshlrev_b64 v[4:5], 2, v[0:1]
	v_mov_b32_e32 v9, v171
	v_lshl_add_u64 v[6:7], s[42:43], 0, v[4:5]
	v_lshl_add_u64 v[4:5], s[44:45], 0, v[4:5]
	global_load_dwordx2 v[2:3], v[2:3], off
	s_lshl_b32 s0, s18, 6
	global_load_dword v0, v[6:7], off
	global_load_dword v16, v[4:5], off
	v_ashrrev_i32_e32 v4, 3, v9
	v_and_b32_e32 v4, -8, v4
	s_add_i32 s54, s0, 0xffff0000
	v_ashrrev_i32_e32 v5, 31, v4
	v_lshl_add_u64 v[10:11], v[4:5], 0, s[54:55]
	v_mbcnt_hi_u32_b32 v4, -1, v195
	v_and_b32_e32 v5, 64, v4
	v_add_u32_e32 v5, 64, v5
	v_xor_b32_e32 v6, 32, v4
	v_cmp_lt_i32_e32 vcc, v6, v5
	v_lshlrev_b32_e32 v12, 2, v8
	s_mov_b64 s[2:3], 0x1da2d000
	v_cndmask_b32_e32 v6, v4, v6, vcc
	v_lshlrev_b32_e32 v17, 2, v6
	v_xor_b32_e32 v6, 16, v4
	v_cmp_lt_i32_e32 vcc, v6, v5
	v_cmp_gt_u32_e64 s[0:1], 8, v8
	v_lshlrev_b64 v[8:9], 8, v[10:11]
	v_cndmask_b32_e32 v6, v4, v6, vcc
	v_lshlrev_b32_e32 v18, 2, v6
	v_xor_b32_e32 v6, 8, v4
	v_cmp_lt_i32_e32 vcc, v6, v5
	v_or_b32_e32 v8, v8, v12
	s_mov_b32 s10, 0x3c800000
	v_cndmask_b32_e32 v6, v4, v6, vcc
	v_lshlrev_b32_e32 v19, 2, v6
	v_xor_b32_e32 v6, 4, v4
	v_cmp_lt_i32_e32 vcc, v6, v5
	s_mov_b32 s4, 8
	s_brev_b32 s11, 60
	v_cndmask_b32_e32 v6, v4, v6, vcc
	v_lshlrev_b32_e32 v20, 2, v6
	v_xor_b32_e32 v6, 2, v4
	v_cmp_lt_i32_e32 vcc, v6, v5
	s_mov_b64 s[12:13], 0x1fa0
	v_readlane_b32 s37, v253, 17
	v_cndmask_b32_e32 v6, v4, v6, vcc
	v_lshlrev_b32_e32 v21, 2, v6
	v_xor_b32_e32 v6, 1, v4
	v_cmp_lt_i32_e32 vcc, v6, v5
	v_readlane_b32 s38, v253, 18
	v_readlane_b32 s39, v253, 19
	v_cndmask_b32_e32 v4, v4, v6, vcc
	v_lshlrev_b32_e32 v22, 2, v4
	v_lshlrev_b64 v[4:5], 5, v[10:11]
	v_or_b32_e32 v4, v4, v12
	v_lshlrev_b64 v[6:7], 7, v[10:11]
	v_lshl_add_u64 v[4:5], v[4:5], 0, s[2:3]
	v_and_b32_e32 v24, 31, v10
	v_and_b32_e32 v6, 0xfffff000, v6
	v_lshl_or_b32 v6, v24, 4, v6
	v_and_b32_e32 v24, 0x70, v23
	v_lshl_or_b32 v6, v24, 5, v6
	v_and_b32_e32 v24, 14, v23
	v_or_b32_e32 v6, v6, v24
	s_mov_b64 s[2:3], 0x1ca2d000
	v_lshl_add_u64 v[6:7], v[6:7], 0, s[2:3]
	s_mov_b64 s[2:3], 0x1ce2d000
	v_lshl_add_u64 v[8:9], v[8:9], 0, s[2:3]
	v_mad_u64_u32 v[14:15], s[2:3], v10, s91, 0
	v_mad_i32_i24 v11, v11, s91, v15
	v_or_b32_e32 v10, v14, v12
	s_mov_b64 s[2:3], 0x4daee10
	v_lshl_add_u64 v[12:13], v[10:11], 0, s[2:3]
	v_or_b32_e32 v10, v14, v23
	v_readlane_b32 s46, v253, 26
	v_readlane_b32 s47, v253, 27
	v_readlane_b32 s48, v253, 28
	v_readlane_b32 s49, v253, 29
	v_readlane_b32 s50, v253, 30
	v_readlane_b32 s51, v253, 31
	s_branch .LBB0_244
.LBB0_243:
	s_or_b64 exec, exec, s[2:3]
	s_mov_b64 s[2:3], 16
	s_add_i32 s4, s4, -1
	v_lshl_add_u64 v[6:7], v[6:7], 0, s[2:3]
	s_mov_b64 s[2:3], 0x100
	v_lshl_add_u64 v[4:5], v[4:5], 0, 32
	v_lshl_add_u64 v[8:9], v[8:9], 0, s[2:3]
	v_lshl_add_u64 v[12:13], v[12:13], 0, s[12:13]
	s_cmp_lg_u32 s4, 0
	v_lshl_add_u64 v[10:11], v[10:11], 0, s[12:13]
	s_cbranch_scc0 .LBB0_246

;   __device__ __forceinline__ u16* KIDX() const { return (u16*)(ws + O_KIDX); }
;   __device__ __forceinline__ float* WIDX() const { return (float*)(ws + O_WIDX); }
; DI void dsa_item(const Params& p, int l, int tile32, int b, char* smem) {
;     ...
;   {
;     bf16x8 qa[4];
;     {
;       const int r = c31, ql = 2 * ((r >> 2) & 1) + (r & 1), hd = ((r & 3) >> 1) + 2 * (r >> 3);
;       const u16* qrow = QX + (tokbase + t0 + ql) * LDQ + 1024 + hd * 64 + 8 * hh;
; #pragma unroll
;       for (int s = 0; s < 4; ++s) qa[s] = *(const bf16x8*)(qrow + 16 * s);
;     }
;     typedef float f32x2 __attribute__((ext_vector_type(2)));
;     f32x2 wq2[8];
;     {
;       const float4* wi = (const float4*)(p.WIDX() + (tokbase + t0 + 2 * hh) * 8);
;       const float4 a0 = wi[0], a1 = wi[1], b0 = wi[2], b1 = wi[3];
;       wq2[0] = f32x2{a0.x, b0.x}; wq2[1] = f32x2{a0.y, b0.y}; wq2[2] = f32x2{a0.z, b0.z}; wq2[3] = f32x2{a0.w, b0.w};
;       wq2[4] = f32x2{a1.x, b1.x}; wq2[5] = f32x2{a1.y, b1.y}; wq2[6] = f32x2{a1.z, b1.z}; wq2[7] = f32x2{a1.w, b1.w};
;     }
;     const int qpos0 = t0 + 2 * hh;
;     const int nkt = ((t0 + 3) >> 5) + 1;
;     const u32 lmask = (1u << c31) - 1u;
; #pragma unroll 1
;     for (int rep = 0; rep < DUP_DSA1; ++rep) {
;     cnt0 = cnt1 = cnt2 = cnt3 = 0;
;     u32 tau0 = 0u, tau1 = 0u, tau2 = 0u, tau3 = 0u;
;     bf16x8 kn[4][4];
;     {
; #pragma unroll
;       for (int t = 0; t < 4; ++t) {
;         const u16* krow = p.KIDX() + (tokbase + t * 32 + c31) * 64 + 8 * hh;
; #pragma unroll
;         for (int s = 0; s < 4; ++s) kn[t][s] = *(const bf16x8*)(krow + 16 * s);
;       }
;     }
;     const int ngrp = (nkt + 3) >> 2;
.LBB0_369:
	s_cmp_gt_i32 s2, 0
	s_cbranch_scc0 .LBB0_594
	s_add_i32 s2, s2, -1
	s_lshr_b32 s61, s2, 1
	s_bitcmp1_b32 s2, 0
	s_cselect_b64 s[2:3], -1, 0
	s_and_b64 vcc, exec, s[2:3]
	s_cbranch_vccz .LBB0_575
	v_mov_b32_e32 v189, v171
	s_lshl_b32 s0, s60, 4
	s_and_b32 s0, s0, 0x7fffffe0
	v_ashrrev_i32_e32 v0, 6, v189
	s_lshl_b32 s1, s61, 7
	v_lshlrev_b32_e32 v2, 2, v0
	s_add_i32 s1, s1, s0
	v_subrev_u32_e32 v2, s1, v2
	v_add_u32_e32 v6, 0x3fe0, v2
	s_lshl_b32 s0, s60, 14
	v_ashrrev_i32_e32 v2, 5, v6
	v_bfe_u32 v191, v189, 5, 1
	s_and_b32 s68, s0, 0x4000
	s_movk_i32 s0, 0x4400
	v_add_u32_e32 v2, 4, v2
	v_and_b32_e32 v188, 63, v189
	s_mov_b32 s69, s55
	v_mul_lo_u32 v190, v0, s0
	v_ashrrev_i32_e32 v7, 31, v6
	v_lshlrev_b32_e32 v0, 3, v191
	v_ashrrev_i32_e32 v210, 2, v2
	s_waitcnt vmcnt(17)
	v_lshl_add_u64 v[166:167], v[6:7], 0, s[68:69]
	v_and_b32_e32 v192, 31, v189
	v_cmp_lt_i32_e32 vcc, -1, v210
	v_or_b32_e32 v208, 0x80, v188
	v_or_b32_e32 v209, 64, v188
	v_or_b32_e32 v193, 0xc0, v188
	v_mov_b32_e32 v173, 0
	v_lshlrev_b32_e32 v168, 1, v0
	v_mov_b32_e32 v186, 0
	v_mov_b32_e32 v187, 0
	v_mov_b32_e32 v175, 0
	s_and_saveexec_b64 s[70:71], vcc
	s_cbranch_execz .LBB0_523
	v_lshrrev_b32_e32 v0, 1, v189
	v_lshrrev_b32_e32 v4, 2, v189
	v_and_b32_e32 v2, 2, v0
	v_and_b32_e32 v3, 1, v189
	v_and_b32_e32 v4, 6, v4
	v_and_or_b32 v0, v0, 1, v4
	v_or3_b32 v4, v2, v3, v166
	v_mov_b64_e32 v[2:3], s[86:87]
	s_movk_i32 s2, 0xc80
	v_mad_u64_u32 v[2:3], s[0:1], v4, s2, v[2:3]
	v_mad_i32_i24 v3, v167, s2, v3
	v_lshlrev_b32_e32 v0, 7, v0
	v_lshl_add_u64 v[2:3], v[2:3], 0, v[0:1]
	v_mov_b32_e32 v169, v1
	v_lshl_add_u64 v[2:3], v[2:3], 0, v[168:169]
	v_lshlrev_b32_e32 v7, 1, v191
	global_load_dwordx4 v[18:21], v[2:3], off offset:2048
	global_load_dwordx4 v[22:25], v[2:3], off offset:2080
	global_load_dwordx4 v[26:29], v[2:3], off offset:2112
	global_load_dwordx4 v[30:33], v[2:3], off offset:2144
	v_or_b32_e32 v2, v166, v7
	v_mov_b32_e32 v3, v167
	v_readlane_b32 s0, v253, 56
	v_lshlrev_b64 v[2:3], 5, v[2:3]
	v_readlane_b32 s1, v253, 57
	v_mov_b32_e32 v211, s68
	v_lshlrev_b32_e32 v0, 7, v211
	v_lshl_add_u64 v[2:3], s[0:1], 0, v[2:3]
	v_readlane_b32 s0, v253, 54
	v_readlane_b32 s1, v253, 55
	global_load_dwordx4 v[34:37], v[2:3], off offset:48
	global_load_dwordx4 v[38:41], v[2:3], off offset:32
	global_load_dwordx4 v[8:11], v[2:3], off offset:16
	global_load_dwordx4 v[12:15], v[2:3], off
	v_lshlrev_b32_e32 v226, 4, v192
	v_lshl_or_b32 v226, v191, 9, v226
	v_mov_b32_e32 v227, 0
	v_lshl_add_u64 v[176:177], s[0:1], 0, v[226:227]
	v_lshl_add_u64 v[2:3], v[176:177], 0, v[0:1]
	v_add_co_u32_e32 v4, vcc, 0x3000, v2
	v_lshlrev_b32_e64 v0, v192, -1
	s_nop 0
	v_addc_co_u32_e32 v5, vcc, 0, v3, vcc
	global_load_dwordx4 v[42:45], v[4:5], off offset:3072
	global_load_dwordx4 v[46:49], v[4:5], off offset:2048
	global_load_dwordx4 v[50:53], v[4:5], off offset:1024
	global_load_dwordx4 v[54:57], v[4:5], off
	v_add_co_u32_e32 v4, vcc, 0x2000, v2
	v_or_b32_e32 v217, v6, v7
	s_nop 0
	v_addc_co_u32_e32 v5, vcc, 0, v3, vcc
	v_add_co_u32_e32 v16, vcc, 0x1000, v2
	global_load_dwordx4 v[58:61], v[4:5], off offset:3072
	global_load_dwordx4 v[62:65], v[4:5], off offset:2048
	global_load_dwordx4 v[66:69], v[4:5], off offset:1024
	global_load_dwordx4 v[70:73], v[4:5], off
	v_addc_co_u32_e32 v17, vcc, 0, v3, vcc
	global_load_dwordx4 v[74:77], v[16:17], off offset:3072
	global_load_dwordx4 v[78:81], v[16:17], off offset:2048
	global_load_dwordx4 v[90:93], v[2:3], off offset:3072
	global_load_dwordx4 v[94:97], v[2:3], off offset:2048
	global_load_dwordx4 v[98:101], v[2:3], off offset:1024
	s_nop 0
	global_load_dwordx4 v[2:5], v[2:3], off
	s_nop 0
	global_load_dwordx4 v[82:85], v[16:17], off offset:1024
	global_load_dwordx4 v[86:89], v[16:17], off
	v_or_b32_e32 v169, 0x100, v188
	v_or_b32_e32 v212, 0x180, v188
	v_or_b32_e32 v213, 0x200, v188
	v_mul_u32_u24_e32 v214, 0x500, v191
	v_or_b32_e32 v215, 0x140, v188
	v_or_b32_e32 v216, 0x1c0, v188
	v_not_b32_e32 v218, v0
	v_or_b32_e32 v219, 1, v217
	v_or_b32_e32 v220, 0x240, v188
	v_cmp_gt_u32_e32 vcc, 32, v188
	v_mov_b32_e32 v173, 0
	s_mov_b64 s[72:73], 0
	s_mov_b32 s54, 0
	v_mov_b32_e32 v186, 0
	v_mov_b32_e32 v187, 0
	v_mov_b32_e32 v175, 0
	v_mov_b32_e32 v224, 0
	v_mov_b32_e32 v222, 0
	v_mov_b32_e32 v223, 0
	v_mov_b32_e32 v221, 0
	s_waitcnt vmcnt(19)
	v_mov_b32_e32 v183, v34
	s_waitcnt vmcnt(18)
	v_mov_b32_e32 v179, v38
	v_mov_b32_e32 v181, v40
	s_waitcnt vmcnt(16)
	v_mov_b32_e32 v178, v12
	v_mov_b32_e32 v38, v13
	v_mov_b32_e32 v180, v14
	v_mov_b32_e32 v40, v15
	v_mov_b32_e32 v182, v8
	v_mov_b32_e32 v34, v9
	v_mov_b32_e32 v184, v10
	v_mov_b32_e32 v185, v36
	v_mov_b32_e32 v36, v11
	s_branch .LBB0_376

; DI u32 dsa_prune(u32* ck, u16* ci, int cnt, u32 tau_old, bool exact, int ln, int& newcnt) {
;     ...
;   u32 L = tau_old + 1u, H = mx + 1u;
;   int curL = cnt;
;   while ((exact || curL > 384) && (H - L) > 1u) {
;     const u32 mid = L + ((H - L) >> 1);
;     int c = 0;
; #pragma unroll
;     for (int j = 0; j < 10; ++j) c += __popcll(__ballot(kv[j] >= mid));
;     if (c >= 256) { L = mid; curL = c; } else H = mid;
;   }
.LBB0_424:
	v_sub_u32_e32 v117, v115, v10
	v_cmp_lt_u32_e64 s[8:9], 1, v117
	v_mov_b32_e32 v116, 0x100
	s_or_b64 s[14:15], s[14:15], exec
	s_and_saveexec_b64 s[16:17], s[8:9]
	s_cbranch_execz .LBB0_423
	v_lshrrev_b32_e32 v116, 1, v117
	v_add_u32_e32 v117, v116, v10
	v_cmp_ge_u32_e64 s[8:9], v114, v117
	s_bcnt1_i32_b64 s18, s[8:9]
	v_cmp_ge_u32_e64 s[8:9], v112, v117
	s_bcnt1_i32_b64 s8, s[8:9]
	s_add_i32 s18, s8, s18
	v_cmp_ge_u32_e64 s[8:9], v110, v117
	s_bcnt1_i32_b64 s8, s[8:9]
	s_add_i32 s18, s18, s8
	v_cmp_ge_u32_e64 s[8:9], v108, v117
	s_bcnt1_i32_b64 s8, s[8:9]
	s_add_i32 s18, s18, s8
	v_cmp_ge_u32_e64 s[8:9], v106, v117
	s_bcnt1_i32_b64 s8, s[8:9]
	s_add_i32 s18, s18, s8
	v_cmp_ge_u32_e64 s[8:9], v104, v117
	s_bcnt1_i32_b64 s8, s[8:9]
	s_add_i32 s18, s18, s8
	v_cmp_ge_u32_e64 s[8:9], v102, v117
	s_bcnt1_i32_b64 s8, s[8:9]
	s_add_i32 s18, s18, s8
	v_cmp_ge_u32_e64 s[8:9], v16, v117
	s_bcnt1_i32_b64 s8, s[8:9]
	s_add_i32 s18, s18, s8
	v_cmp_ge_u32_e64 s[8:9], v14, v117
	s_bcnt1_i32_b64 s8, s[8:9]
	s_add_i32 s18, s18, s8
	v_cmp_ge_u32_e64 s[8:9], v12, v117
	s_bcnt1_i32_b64 s8, s[8:9]
	s_add_i32 s8, s18, s8
	s_cmpk_gt_u32 s8, 0xff
	v_mov_b32_e32 v116, s8
	s_cselect_b64 s[8:9], -1, 0
	v_cndmask_b32_e64 v116, v6, v116, s[8:9]
	v_cndmask_b32_e64 v115, v117, v115, s[8:9]
	v_cndmask_b32_e64 v10, v10, v117, s[8:9]
	s_movk_i32 s8, 0x181
	v_cmp_gt_i32_e64 s[8:9], s8, v116
	s_xor_b64 s[18:19], s[2:3], -1
	s_and_b64 s[8:9], s[18:19], s[8:9]
	v_cmp_eq_u32_e64 s[18:19], v116, v202
	s_or_b64 s[8:9], s[8:9], s[18:19]
	s_andn2_b64 s[14:15], s[14:15], exec
	s_and_b64 s[8:9], s[8:9], exec
	s_or_b64 s[14:15], s[14:15], s[8:9]
	v_mov_b32_e32 v6, v116
	s_branch .LBB0_423

;   __device__ __forceinline__ u16* KIDX() const { return (u16*)(ws + O_KIDX); }
; DI void dsa_item(const Params& p, int l, int tile32, int b, char* smem) {
;     ...
;       bf16x8 kc[4][4];
; #pragma unroll
;       for (int t = 0; t < 4; ++t)
; #pragma unroll
;         for (int s = 0; s < 4; ++s) kc[t][s] = kn[t][s];
;       if (g + 1 < ngrp) {
; #pragma unroll
;         for (int t = 0; t < 4; ++t) {
;           const u16* krow = p.KIDX() + (tokbase + (g + 1) * 128 + t * 32 + c31) * 64 + 8 * hh;
; #pragma unroll
;           for (int s = 0; s < 4; ++s) kn[t][s] = *(const bf16x8*)(krow + 16 * s);
;         }
;       }
.LBB0_496:
	s_or_b64 exec, exec, s[96:97]
	s_add_i32 s12, s54, 1
	s_and_saveexec_b64 s[8:9], s[0:1]
	s_cbranch_execz .LBB0_375
	s_waitcnt vmcnt(2)
	v_mov_b64_e32 v[104:105], v[4:5]
	v_mov_b64_e32 v[108:109], v[100:101]
	v_mov_b64_e32 v[112:113], v[96:97]
	s_waitcnt lgkmcnt(0)
	v_mov_b64_e32 v[116:117], v[92:93]
	s_waitcnt vmcnt(0)
	v_mov_b64_e32 v[120:121], v[88:89]
	v_mov_b64_e32 v[124:125], v[84:85]
	v_mov_b64_e32 v[128:129], v[80:81]
	v_mov_b64_e32 v[132:133], v[76:77]
	v_mov_b64_e32 v[136:137], v[72:73]
	v_mov_b64_e32 v[140:141], v[68:69]
	v_mov_b64_e32 v[144:145], v[64:65]
	v_mov_b64_e32 v[148:149], v[60:61]
	v_mov_b64_e32 v[152:153], v[56:57]
	v_mov_b64_e32 v[156:157], v[52:53]
	v_mov_b64_e32 v[160:161], v[48:49]
	v_mov_b64_e32 v[164:165], v[44:45]
	v_cmp_lt_i32_e64 s[0:1], s12, v210
	v_mov_b64_e32 v[102:103], v[2:3]
	v_mov_b64_e32 v[106:107], v[98:99]
	v_mov_b64_e32 v[110:111], v[94:95]
	v_mov_b64_e32 v[114:115], v[90:91]
	v_mov_b64_e32 v[118:119], v[86:87]
	v_mov_b64_e32 v[122:123], v[82:83]
	v_mov_b64_e32 v[126:127], v[78:79]
	v_mov_b64_e32 v[130:131], v[74:75]
	v_mov_b64_e32 v[134:135], v[70:71]
	v_mov_b64_e32 v[138:139], v[66:67]
	v_mov_b64_e32 v[142:143], v[62:63]
	v_mov_b64_e32 v[146:147], v[58:59]
	v_mov_b64_e32 v[150:151], v[54:55]
	v_mov_b64_e32 v[154:155], v[50:51]
	v_mov_b64_e32 v[158:159], v[46:47]
	v_mov_b64_e32 v[162:163], v[42:43]
	s_and_saveexec_b64 s[2:3], s[0:1]
	s_cbranch_execz .LBB0_499
	v_lshl_add_u32 v0, s12, 7, v211
	v_lshlrev_b64 v[6:7], 7, v[0:1]
	v_lshl_add_u64 v[6:7], v[176:177], 0, v[6:7]
	global_load_dwordx4 v[102:105], v[6:7], off
	global_load_dwordx4 v[106:109], v[6:7], off offset:1024
	global_load_dwordx4 v[110:113], v[6:7], off offset:2048
	global_load_dwordx4 v[114:117], v[6:7], off offset:3072
	v_or_b32_e32 v6, 32, v0
	v_mov_b32_e32 v7, v1
	v_lshlrev_b64 v[6:7], 7, v[6:7]
	v_lshl_add_u64 v[6:7], v[176:177], 0, v[6:7]
	global_load_dwordx4 v[118:121], v[6:7], off
	global_load_dwordx4 v[122:125], v[6:7], off offset:1024
	global_load_dwordx4 v[126:129], v[6:7], off offset:2048
	global_load_dwordx4 v[130:133], v[6:7], off offset:3072
	v_or_b32_e32 v6, 64, v0
	v_mov_b32_e32 v7, v1
	v_lshlrev_b64 v[6:7], 7, v[6:7]
	v_lshl_add_u64 v[6:7], v[176:177], 0, v[6:7]
	v_or_b32_e32 v0, 0x60, v0
	global_load_dwordx4 v[134:137], v[6:7], off
	global_load_dwordx4 v[138:141], v[6:7], off offset:1024
	global_load_dwordx4 v[142:145], v[6:7], off offset:2048
	global_load_dwordx4 v[146:149], v[6:7], off offset:3072
	v_lshlrev_b64 v[6:7], 7, v[0:1]
	v_lshl_add_u64 v[6:7], v[176:177], 0, v[6:7]
	global_load_dwordx4 v[150:153], v[6:7], off
	global_load_dwordx4 v[154:157], v[6:7], off offset:1024
	global_load_dwordx4 v[158:161], v[6:7], off offset:2048
	global_load_dwordx4 v[162:165], v[6:7], off offset:3072
